# P0 reorder v2: (d) items split 12 / 9 / 4 per wave for waves 4-7 / fast-(e) waves / slow-(e) waves
# speedup vs baseline: 1.0321x; 1.0040x over previous
.Lp0_d_entry:
	v_mov_b32_e32 v2, v220
	s_and_b32 s99, s98, 7
	s_lshr_b32 s100, s98, 3
	s_lshl_b32 s100, s100, 2
	s_add_i32 s0, s100, s99
	s_cmp_lt_u32 s99, 4
	s_cbranch_scc1 .Lp0_d_lo
	s_add_i32 s0, s0, -4
	s_movk_i32 s98, 0x400
	s_mov_b32 s101, 0x2fff
	s_branch .Lp0_d_go
.Lp0_d_lo:
	s_and_b32 s100, s0, 2
	s_lshl_b32 s100, s100, 7
	s_xor_b32 s0, s0, s100
	s_lshr_b32 s100, s0, 1
	s_and_b32 s100, s100, 0x100
	s_and_b32 s99, s0, 0xff
	s_or_b32 s99, s99, s100
	s_mov_b32 s101, 0x41ff
	s_bitcmp1_b32 s0, 8
	s_mov_b32 s0, 0x3000
	s_cselect_b32 s0, 0x4200, s0
	s_cselect_b32 s101, 0x49ff, s101
	s_add_i32 s0, s0, s99
	s_movk_i32 s98, 0x200
.Lp0_d_go:
	v_lshrrev_b32_e32 v16, 5, v168
	s_movk_i32 s4, 0x84
	v_mov_b32_e32 v4, 0x630
	v_mad_u32_u24 v5, v16, s4, v4
	v_mov_b32_e32 v4, 0xc60
	v_mad_u32_u24 v6, v16, s4, v4
	v_mov_b32_e32 v4, 0x1290
	v_mad_u32_u24 v7, v16, s4, v4
	v_mov_b32_e32 v4, 0x18c0
	v_and_b32_e32 v0, 31, v2
	v_mad_u32_u24 v8, v16, s4, v4
	v_lshlrev_b32_e32 v4, 3, v168
	v_lshl_add_u32 v2, v0, 2, s7
	v_mul_u32_u24_e32 v3, 0x84, v16
	v_lshrrev_b32_e32 v48, 3, v168
	v_and_b32_e32 v4, 56, v4
	s_add_u32 s11, s12, 0x400000
	v_mul_u32_u24_e32 v9, 0x84, v4
	v_lshlrev_b32_e32 v10, 2, v48
	v_add_u32_e32 v57, v2, v3
	v_add_u32_e32 v58, v2, v5
	v_add_u32_e32 v59, v2, v6
	v_add_u32_e32 v60, v2, v7
	v_add_u32_e32 v61, v2, v8
	s_addc_u32 s30, s13, 0
	v_mov_b32_e32 v1, 0
	v_or_b32_e32 v17, 2, v16
	v_or_b32_e32 v18, 4, v16
	v_or_b32_e32 v19, 6, v16
	v_or_b32_e32 v20, 8, v16
	v_or_b32_e32 v21, 10, v16
	v_or_b32_e32 v22, 12, v16
	v_or_b32_e32 v23, 14, v16
	v_or_b32_e32 v24, 16, v16
	v_or_b32_e32 v25, 18, v16
	v_or_b32_e32 v26, 20, v16
	v_or_b32_e32 v27, 22, v16
	v_or_b32_e32 v28, 24, v16
	v_or_b32_e32 v29, 26, v16
	v_or_b32_e32 v30, 28, v16
	v_or_b32_e32 v31, 30, v16
	v_or_b32_e32 v32, 32, v16
	v_or_b32_e32 v33, 34, v16
	v_or_b32_e32 v34, 36, v16
	v_or_b32_e32 v35, 38, v16
	v_or_b32_e32 v36, 40, v16
	v_or_b32_e32 v37, 42, v16
	v_or_b32_e32 v38, 44, v16
	v_or_b32_e32 v39, 46, v16
	v_or_b32_e32 v40, 48, v16
	v_or_b32_e32 v41, 50, v16
	v_or_b32_e32 v42, 52, v16
	v_or_b32_e32 v43, 54, v16
	v_or_b32_e32 v44, 56, v16
	v_or_b32_e32 v45, 58, v16
	v_or_b32_e32 v46, 60, v16
	v_or_b32_e32 v47, 62, v16
	v_add3_u32 v49, s7, v9, v10
	v_or_b32_e32 v50, 8, v48
	v_or_b32_e32 v51, 16, v48
	v_or_b32_e32 v52, 24, v48
	v_or_b32_e32 v53, 0x500, v48
	v_or_b32_e32 v54, 0x508, v48
	v_or_b32_e32 v55, 0x510, v48
	v_or_b32_e32 v56, 0x518, v48
	s_lshl_b32 s31, s0, 5
	s_lshl_b32 s34, s98, 5
	s_lshl_b32 s35, s0, 1
	s_lshl_b32 s36, s98, 1
	s_movk_i32 s37, 0xaff
	s_add_i32 s38, 0, 0x20070
	s_add_i32 s39, 0, 0x20074
	s_mov_b64 s[8:9], 0x200000
	s_mov_b64 s[14:15], 0x2400400
	s_add_i32 s40, 0, 0x20068
	s_add_i32 s41, 0, 0x2006c
	s_mov_b64 s[18:19], 0x2100000
	s_mov_b32 s42, 0x7ffffe00
	s_add_i32 s43, 0, 0x20060
	s_add_i32 s44, 0, 0x20064
	s_mov_b64 s[20:21], 0x1b80000
	s_add_i32 s45, 0, 0x20050
	s_add_i32 s46, 0, 0x20054
	s_mov_b64 s[22:23], 0xb00000
	s_add_i32 s47, 0, 0x20058
	s_add_i32 s48, 0, 0x2005c
	s_mov_b64 s[24:25], 0x1080000
	s_add_i32 s49, 0, 0x20048
	s_add_i32 s50, 0, 0x2004c
	v_lshlrev_b32_e32 v2, 2, v0
	v_add_u32_e32 v62, 0x400, v57
	v_add_u32_e32 v63, 0x400, v58
	v_add_u32_e32 v64, 0x400, v59
	v_add_u32_e32 v65, 0x400, v60
	v_add_u32_e32 v66, 0x400, v61
	v_lshlrev_b32_e32 v0, 1, v4
	v_mov_b32_e32 v67, 0xfffff500
	v_mov_b32_e32 v68, 0x80
	v_mov_b32_e32 v69, 0x67
	v_mov_b32_e32 v70, 0x6f
	v_mov_b32_e32 v71, 0x77
	v_mov_b32_e32 v72, 0x7f
	s_mov_b32 s51, s0
	s_branch .LBB0_43
.LBB0_42:
	s_add_i32 s51, s51, s98
	s_add_i32 s31, s31, s34
	s_add_i32 s35, s35, s36
	s_cmp_gt_i32 s51, s101
	s_cbranch_scc1 .LBB0_112
